# nt (non-temporal) hint on the 32 final f32 output stores of P11 (never re-read)
# speedup vs baseline: 1.0089x; 1.0058x over previous
.LBB0_1359:
	s_or_b64 exec, exec, s[20:21]
	v_lshlrev_b64 v[80:81], 2, v[190:191]
	v_lshl_add_u64 v[0:1], s[56:57], 0, v[80:81]
	global_load_dwordx4 v[12:15], v[0:1], off
	global_load_dwordx4 v[8:11], v[0:1], off offset:16
	global_load_dwordx4 v[4:7], v[0:1], off offset:512
	s_nop 0
	global_load_dwordx4 v[0:3], v[0:1], off offset:528
	v_lshlrev_b64 v[82:83], 12, v[192:193]
	s_waitcnt lgkmcnt(0)
	s_barrier
	v_lshl_add_u64 v[82:83], s[58:59], 0, v[82:83]
	ds_read2_b32 v[120:121], v207 offset1:16
	v_lshl_add_u64 v[138:139], v[82:83], 0, v[80:81]
	ds_read2_b32 v[82:83], v207 offset0:32 offset1:48
	v_lshlrev_b64 v[84:85], 12, v[188:189]
	v_lshlrev_b64 v[86:87], 12, v[186:187]
	v_lshl_add_u64 v[84:85], s[58:59], 0, v[84:85]
	v_lshl_add_u64 v[86:87], s[58:59], 0, v[86:87]
	v_lshl_add_u64 v[140:141], v[84:85], 0, v[80:81]
	s_waitcnt lgkmcnt(1)
	v_pk_mul_f32 v[84:85], v[134:135], v[120:121] op_sel_hi:[1,0]
	v_pk_mul_f32 v[122:123], v[132:133], v[120:121] op_sel_hi:[1,0]
	v_pk_mul_f32 v[126:127], v[126:127], v[120:121] op_sel_hi:[1,0]
	v_pk_mul_f32 v[124:125], v[124:125], v[120:121] op_sel_hi:[1,0]
	v_pk_mul_f32 v[118:119], v[118:119], v[120:121] op_sel_hi:[1,0]
	v_pk_mul_f32 v[116:117], v[116:117], v[120:121] op_sel_hi:[1,0]
	v_pk_mul_f32 v[114:115], v[114:115], v[120:121] op_sel_hi:[1,0]
	v_pk_mul_f32 v[112:113], v[112:113], v[120:121] op_sel_hi:[1,0]
	v_mov_b32_e32 v120, v121
	v_lshlrev_b64 v[136:137], 12, v[184:185]
	v_lshl_add_u64 v[86:87], v[86:87], 0, v[80:81]
	s_waitcnt lgkmcnt(0)
	v_pk_mul_f32 v[128:129], v[94:95], v[82:83] op_sel_hi:[1,0]
	v_pk_mul_f32 v[130:131], v[92:93], v[82:83] op_sel_hi:[1,0]
	v_pk_mul_f32 v[132:133], v[156:157], v[82:83] op_sel_hi:[1,0]
	v_pk_mul_f32 v[134:135], v[158:159], v[82:83] op_sel_hi:[1,0]
	v_pk_mul_f32 v[142:143], v[152:153], v[82:83] op_sel_hi:[1,0]
	v_pk_mul_f32 v[152:153], v[160:161], v[82:83] op_sel_hi:[1,0]
	v_pk_mul_f32 v[156:157], v[164:165], v[82:83] op_sel_hi:[1,0]
	v_pk_mul_f32 v[158:159], v[194:195], v[82:83] op_sel_hi:[1,0]
	v_mov_b32_e32 v160, v83
	v_pk_mul_f32 v[110:111], v[110:111], v[120:121] op_sel_hi:[1,0]
	v_pk_mul_f32 v[108:109], v[108:109], v[120:121] op_sel_hi:[1,0]
	v_pk_mul_f32 v[164:165], v[106:107], v[120:121] op_sel_hi:[1,0]
	v_pk_mul_f32 v[184:185], v[104:105], v[120:121] op_sel_hi:[1,0]
	v_pk_mul_f32 v[186:187], v[102:103], v[120:121] op_sel_hi:[1,0]
	v_pk_mul_f32 v[188:189], v[100:101], v[120:121] op_sel_hi:[1,0]
	v_pk_mul_f32 v[190:191], v[98:99], v[120:121] op_sel_hi:[1,0]
	v_pk_mul_f32 v[120:121], v[96:97], v[120:121] op_sel_hi:[1,0]
	v_pk_mul_f32 v[192:193], v[200:201], v[160:161] op_sel_hi:[1,0]
	s_and_b64 vcc, exec, s[6:7]
	s_mov_b64 s[4:5], -1
	s_waitcnt vmcnt(3)
	v_pk_mul_f32 v[84:85], v[14:15], v[84:85]
	v_pk_mul_f32 v[82:83], v[12:13], v[122:123]
	s_waitcnt vmcnt(2)
	v_pk_mul_f32 v[94:95], v[10:11], v[126:127]
	v_pk_mul_f32 v[92:93], v[8:9], v[124:125]
	s_waitcnt vmcnt(1)
	v_pk_mul_f32 v[98:99], v[6:7], v[118:119]
	v_pk_mul_f32 v[96:97], v[4:5], v[116:117]
	s_waitcnt vmcnt(0)
	v_pk_mul_f32 v[102:103], v[2:3], v[114:115]
	v_pk_mul_f32 v[100:101], v[0:1], v[112:113]
	v_pk_mul_f32 v[106:107], v[14:15], v[110:111]
	v_pk_mul_f32 v[104:105], v[12:13], v[108:109]
	v_pk_mul_f32 v[110:111], v[10:11], v[164:165]
	v_pk_mul_f32 v[108:109], v[8:9], v[184:185]
	v_pk_mul_f32 v[114:115], v[6:7], v[186:187]
	v_pk_mul_f32 v[112:113], v[4:5], v[188:189]
	v_pk_mul_f32 v[118:119], v[2:3], v[190:191]
	v_pk_mul_f32 v[116:117], v[0:1], v[120:121]
	v_pk_mul_f32 v[122:123], v[14:15], v[128:129]
	v_pk_mul_f32 v[120:121], v[12:13], v[130:131]
	v_pk_mul_f32 v[126:127], v[10:11], v[132:133]
	v_pk_mul_f32 v[124:125], v[8:9], v[134:135]
	v_pk_mul_f32 v[130:131], v[6:7], v[142:143]
	v_pk_mul_f32 v[128:129], v[4:5], v[152:153]
	v_pk_mul_f32 v[134:135], v[2:3], v[156:157]
	v_pk_mul_f32 v[132:133], v[0:1], v[158:159]
	global_store_dwordx4 v[138:139], v[82:85], off nt
	global_store_dwordx4 v[138:139], v[92:95], off offset:16 nt
	global_store_dwordx4 v[138:139], v[96:99], off offset:512 nt
	global_store_dwordx4 v[138:139], v[100:103], off offset:528 nt
	global_store_dwordx4 v[140:141], v[104:107], off nt
	global_store_dwordx4 v[140:141], v[108:111], off offset:16 nt
	global_store_dwordx4 v[140:141], v[112:115], off offset:512 nt
	global_store_dwordx4 v[140:141], v[116:119], off offset:528 nt
	global_store_dwordx4 v[86:87], v[120:123], off nt
	global_store_dwordx4 v[86:87], v[124:127], off offset:16 nt
	global_store_dwordx4 v[86:87], v[128:131], off offset:512 nt
	global_store_dwordx4 v[86:87], v[132:135], off offset:528 nt
	v_pk_mul_f32 v[82:83], v[148:149], v[160:161] op_sel_hi:[1,0]
	v_lshl_add_u64 v[86:87], s[58:59], 0, v[136:137]
	v_pk_mul_f32 v[84:85], v[14:15], v[192:193]
	v_pk_mul_f32 v[82:83], v[12:13], v[82:83]
	v_lshl_add_u64 v[86:87], v[86:87], 0, v[80:81]
	global_store_dwordx4 v[86:87], v[82:85], off nt
	v_pk_mul_f32 v[92:93], v[154:155], v[160:161] op_sel_hi:[1,0]
	ds_read2_b32 v[94:95], v207 offset0:128 offset1:144
	v_pk_mul_f32 v[82:83], v[150:151], v[160:161] op_sel_hi:[1,0]
	s_waitcnt lgkmcnt(0)
	v_pk_mul_f32 v[50:51], v[50:51], v[94:95] op_sel_hi:[1,0]
	v_pk_mul_f32 v[84:85], v[10:11], v[82:83]
	v_pk_mul_f32 v[82:83], v[8:9], v[92:93]
	global_store_dwordx4 v[86:87], v[82:85], off offset:16 nt
	v_pk_mul_f32 v[92:93], v[166:167], v[160:161] op_sel_hi:[1,0]
	v_pk_mul_f32 v[48:49], v[48:49], v[94:95] op_sel_hi:[1,0]
	v_pk_mul_f32 v[82:83], v[162:163], v[160:161] op_sel_hi:[1,0]
	v_pk_mul_f32 v[50:51], v[2:3], v[50:51]
	v_pk_mul_f32 v[84:85], v[6:7], v[82:83]
	v_pk_mul_f32 v[82:83], v[4:5], v[92:93]
	global_store_dwordx4 v[86:87], v[82:85], off offset:512 nt
	v_pk_mul_f32 v[92:93], v[196:197], v[160:161] op_sel_hi:[1,0]
	v_pk_mul_f32 v[48:49], v[0:1], v[48:49]
	v_pk_mul_f32 v[82:83], v[146:147], v[160:161] op_sel_hi:[1,0]
	v_pk_mul_f32 v[54:55], v[54:55], v[94:95] op_sel_hi:[1,0]
	v_pk_mul_f32 v[84:85], v[2:3], v[82:83]
	v_pk_mul_f32 v[82:83], v[0:1], v[92:93]
	global_store_dwordx4 v[86:87], v[82:85], off offset:528 nt
	v_pk_mul_f32 v[52:53], v[52:53], v[94:95] op_sel_hi:[1,0]
	v_pk_mul_f32 v[54:55], v[6:7], v[54:55]
	v_lshlrev_b64 v[82:83], 12, v[198:199]
	v_lshl_add_u64 v[82:83], s[58:59], 0, v[82:83]
	v_lshl_add_u64 v[82:83], v[82:83], 0, v[80:81]
	global_store_dwordx4 v[82:83], v[48:51], off offset:528 nt
	v_pk_mul_f32 v[52:53], v[4:5], v[52:53]
	global_store_dwordx4 v[82:83], v[52:55], off offset:512 nt
	v_lshlrev_b64 v[48:49], 12, v[144:145]
	v_mov_b32_e32 v50, v95
	v_lshl_add_u64 v[48:49], s[58:59], 0, v[48:49]
	v_pk_mul_f32 v[38:39], v[38:39], v[50:51] op_sel_hi:[1,0]
	v_pk_mul_f32 v[36:37], v[36:37], v[50:51] op_sel_hi:[1,0]
	v_lshl_add_u64 v[48:49], v[48:49], 0, v[80:81]
	v_pk_mul_f32 v[38:39], v[6:7], v[38:39]
	v_pk_mul_f32 v[36:37], v[4:5], v[36:37]
	global_store_dwordx4 v[48:49], v[36:39], off offset:512 nt
	ds_read2_b32 v[36:37], v207 offset0:160 offset1:176
	v_pk_mul_f32 v[34:35], v[34:35], v[50:51] op_sel_hi:[1,0]
	v_pk_mul_f32 v[32:33], v[32:33], v[50:51] op_sel_hi:[1,0]
	v_pk_mul_f32 v[34:35], v[2:3], v[34:35]
	v_pk_mul_f32 v[32:33], v[0:1], v[32:33]
	global_store_dwordx4 v[48:49], v[32:35], off offset:528 nt
	s_waitcnt lgkmcnt(0)
	v_pk_mul_f32 v[18:19], v[18:19], v[36:37] op_sel_hi:[1,0]
	v_pk_mul_f32 v[16:17], v[16:17], v[36:37] op_sel_hi:[1,0]
	v_lshlrev_b64 v[32:33], 12, v[90:91]
	v_lshl_add_u64 v[32:33], s[58:59], 0, v[32:33]
	v_lshl_add_u64 v[32:33], v[32:33], 0, v[80:81]
	v_pk_mul_f32 v[22:23], v[22:23], v[36:37] op_sel_hi:[1,0]
	v_pk_mul_f32 v[20:21], v[20:21], v[36:37] op_sel_hi:[1,0]
	v_pk_mul_f32 v[18:19], v[2:3], v[18:19]
	v_pk_mul_f32 v[16:17], v[0:1], v[16:17]
	v_pk_mul_f32 v[22:23], v[6:7], v[22:23]
	v_pk_mul_f32 v[20:21], v[4:5], v[20:21]
	global_store_dwordx4 v[32:33], v[16:19], off offset:528 nt
	v_pk_mul_f32 v[62:63], v[62:63], v[94:95] op_sel_hi:[1,0]
	v_pk_mul_f32 v[60:61], v[60:61], v[94:95] op_sel_hi:[1,0]
	v_lshlrev_b64 v[16:17], 12, v[88:89]
	v_mov_b32_e32 v18, v37
	v_pk_mul_f32 v[46:47], v[46:47], v[50:51] op_sel_hi:[1,0]
	v_pk_mul_f32 v[44:45], v[44:45], v[50:51] op_sel_hi:[1,0]
	v_pk_mul_f32 v[30:31], v[30:31], v[36:37] op_sel_hi:[1,0]
	v_pk_mul_f32 v[28:29], v[28:29], v[36:37] op_sel_hi:[1,0]
	global_store_dwordx4 v[32:33], v[20:23], off offset:512 nt
	v_lshl_add_u64 v[16:17], s[58:59], 0, v[16:17]
	v_pk_mul_f32 v[62:63], v[14:15], v[62:63]
	v_pk_mul_f32 v[20:21], v[68:69], v[18:19] op_sel_hi:[1,0]
	v_pk_mul_f32 v[22:23], v[72:73], v[18:19] op_sel_hi:[1,0]
	v_pk_mul_f32 v[60:61], v[12:13], v[60:61]
	v_pk_mul_f32 v[46:47], v[14:15], v[46:47]
	v_pk_mul_f32 v[44:45], v[12:13], v[44:45]
	v_pk_mul_f32 v[30:31], v[14:15], v[30:31]
	v_pk_mul_f32 v[28:29], v[12:13], v[28:29]
	v_pk_mul_f32 v[14:15], v[14:15], v[20:21]
	v_pk_mul_f32 v[12:13], v[12:13], v[22:23]
	v_lshl_add_u64 v[16:17], v[16:17], 0, v[80:81]
	global_store_dwordx4 v[82:83], v[60:63], off nt
	v_pk_mul_f32 v[58:59], v[58:59], v[94:95] op_sel_hi:[1,0]
	v_pk_mul_f32 v[56:57], v[56:57], v[94:95] op_sel_hi:[1,0]
	global_store_dwordx4 v[48:49], v[44:47], off nt
	v_pk_mul_f32 v[42:43], v[42:43], v[50:51] op_sel_hi:[1,0]
	v_pk_mul_f32 v[40:41], v[40:41], v[50:51] op_sel_hi:[1,0]
	global_store_dwordx4 v[32:33], v[28:31], off nt
	v_pk_mul_f32 v[26:27], v[26:27], v[36:37] op_sel_hi:[1,0]
	v_pk_mul_f32 v[24:25], v[24:25], v[36:37] op_sel_hi:[1,0]
	global_store_dwordx4 v[16:17], v[12:15], off nt
	v_pk_mul_f32 v[58:59], v[10:11], v[58:59]
	v_pk_mul_f32 v[56:57], v[8:9], v[56:57]
	v_pk_mul_f32 v[12:13], v[70:71], v[18:19] op_sel_hi:[1,0]
	v_pk_mul_f32 v[14:15], v[74:75], v[18:19] op_sel_hi:[1,0]
	v_pk_mul_f32 v[42:43], v[10:11], v[42:43]
	v_pk_mul_f32 v[40:41], v[8:9], v[40:41]
	v_pk_mul_f32 v[26:27], v[10:11], v[26:27]
	v_pk_mul_f32 v[24:25], v[8:9], v[24:25]
	v_pk_mul_f32 v[10:11], v[10:11], v[12:13]
	v_pk_mul_f32 v[8:9], v[8:9], v[14:15]
	global_store_dwordx4 v[82:83], v[56:59], off offset:16 nt
	global_store_dwordx4 v[48:49], v[40:43], off offset:16 nt
	global_store_dwordx4 v[32:33], v[24:27], off offset:16 nt
	global_store_dwordx4 v[16:17], v[8:11], off offset:16 nt
	s_nop 1
	v_pk_mul_f32 v[8:9], v[64:65], v[18:19] op_sel_hi:[1,0]
	v_pk_mul_f32 v[10:11], v[76:77], v[18:19] op_sel_hi:[1,0]
	v_pk_mul_f32 v[6:7], v[6:7], v[8:9]
	v_pk_mul_f32 v[4:5], v[4:5], v[10:11]
	global_store_dwordx4 v[16:17], v[4:7], off offset:512 nt
	s_nop 1
	v_pk_mul_f32 v[4:5], v[66:67], v[18:19] op_sel_hi:[1,0]
	v_pk_mul_f32 v[6:7], v[78:79], v[18:19] op_sel_hi:[1,0]
	v_pk_mul_f32 v[2:3], v[2:3], v[4:5]
	v_pk_mul_f32 v[0:1], v[0:1], v[6:7]
	global_store_dwordx4 v[16:17], v[0:3], off offset:528 nt
	s_waitcnt lgkmcnt(0)
	s_barrier
	s_cbranch_vccnz .LBB0_1313
	s_andn2_b64 vcc, exec, s[2:3]
	s_cbranch_vccnz .LBB0_1312
	s_barrier
	s_branch .LBB0_1312
